# hg_unit Q' row stores: lane roles remapped so each row gets 64B contiguous per instruction; lb_logits loads overlapped; initial cooperative-groups grid sync skipped (XCD barrier census syncs)
# speedup vs baseline: 1.0005x; 1.0005x over previous
; #define LAS __attribute__((address_space(3)))
; __global__ void __launch_bounds__(512, 2) fwd_megakernel(Ptrs Parg) {
;     ...
;     if (threadIdx.x < 4) misc[threadIdx.x] = 0u;
;     if ((threadIdx.x & 63) == 0) { const unsigned hw = (unsigned)__builtin_amdgcn_s_getreg((5 << 11) | 4) & 63u; ((volatile LAS unsigned*)((LAS unsigned char*)lds + pg8::WMAP_OFF))[hw] = threadIdx.x >> 6; }
;     __syncthreads();
;     const XcdBarrier xbar = xcd_barrier_post((unsigned*)Parg.ws, misc);
;     grid.sync();
.LBB0_7:
	s_or_b64 exec, exec, s[4:5]
	v_lshrrev_b32_e32 v2, 20, v0
	v_lshrrev_b32_e32 v0, 10, v0
	v_or_b32_e32 v0, v0, v2
	s_movk_i32 s4, 0x3ff
	v_and_or_b32 v0, v0, s4, v1
	v_cmp_eq_u32_e32 vcc, 0, v0
	s_barrier
	s_and_saveexec_b64 s[4:5], vcc
	s_branch .LBB0_17
	buffer_wbl2 sc1
	s_waitcnt vmcnt(0)
	s_load_dwordx2 s[6:7], s[6:7], 0x58
	v_mov_b32_e32 v2, 0
	s_mov_b64 s[8:9], exec
	v_mbcnt_lo_u32_b32 v1, s8, 0
	v_mbcnt_hi_u32_b32 v1, s9, v1
	s_waitcnt lgkmcnt(0)
	global_load_dword v0, v2, s[6:7] offset:40
	v_cmp_eq_u32_e32 vcc, 0, v1
	s_and_saveexec_b64 s[10:11], vcc
	s_cbranch_execz .LBB0_10
	s_bcnt1_i32_b64 s8, s[8:9]
	v_mov_b32_e32 v3, s8
	global_atomic_add v3, v2, v3, s[6:7] offset:32 sc0

; __device__ __forceinline__ void hg_unit(const Ptrs& P, int l, int b, int hd, int ch, unsigned char* lds, int tid) {
;     ...
;         if (l == 1) { const float a0 = P.lb_logits[hd * 128 + dk], a1 = P.lb_logits[1024 + hd * 128 + dk]; const float mxx = fmaxf(a0, a1); const float e0 = __expf(a0 - mxx), e1 = __expf(a1 - mxx);
;             lb = e1 / (e0 + e1); lb = fminf(fmaxf(lb, 0.f), 1.0f - 1e-4f); }
.LBB0_523:
	v_readlane_b32 s6, v255, 36
	v_readlane_b32 s7, v255, 37
	v_and_b32_e32 v11, 0x7f, v98
	v_mov_b32_e32 v38, 0
	s_andn2_b64 vcc, exec, s[6:7]
	v_mov_b32_e32 v32, 0
	s_cbranch_vccnz .LBB0_525
	v_or_b32_e32 v32, s3, v11
	v_lshlrev_b32_e32 v32, 2, v32
	v_mov_b32_e32 v33, v16
	v_lshl_add_u64 v[34:35], v[2:3], 0, v[32:33]
	v_readfirstlane_b32 s6, v2
	v_readfirstlane_b32 s7, v3
	s_nop 4
	global_load_dword v36, v32, s[6:7]
	v_add_co_u32_e32 v32, vcc, 0x1000, v34
	s_nop 1
	v_addc_co_u32_e32 v33, vcc, 0, v35, vcc
	global_load_dword v32, v[32:33], off
	s_waitcnt vmcnt(1)
	v_max_f32_e32 v34, v36, v36
	s_waitcnt vmcnt(0)
	v_max_f32_e32 v33, v32, v32
	v_max_f32_e32 v33, v34, v33
	v_sub_f32_e32 v34, v36, v33
	v_sub_f32_e32 v32, v32, v33
	v_mul_f32_e32 v34, 0x3fb8aa3b, v34
	v_mul_f32_e32 v32, 0x3fb8aa3b, v32
	v_exp_f32_e32 v34, v34
	v_exp_f32_e32 v32, v32
	s_nop 0
	v_add_f32_e32 v33, v34, v32
	v_div_scale_f32 v34, s[6:7], v33, v33, v32
	v_rcp_f32_e32 v35, v34
	s_nop 0
	v_fma_f32 v36, -v34, v35, 1.0
	v_fmac_f32_e32 v35, v36, v35
	v_div_scale_f32 v36, vcc, v32, v33, v32
	v_mul_f32_e32 v37, v36, v35
	v_fma_f32 v39, -v34, v37, v36
	v_fmac_f32_e32 v37, v39, v35
	v_fma_f32 v34, -v34, v37, v36
	v_div_fmas_f32 v34, v34, v35, v37
	v_div_fixup_f32 v32, v34, v33, v32
	v_max_f32_e32 v32, 0, v32
	v_min_f32_e32 v32, 0x3f7ff972, v32

; __device__ __forceinline__ unsigned pk2(float lo, float hi) { f32x2_t v = {lo, hi}; bf16x2_t b = __builtin_convertvector(v, bf16x2_t); return __builtin_bit_cast(unsigned, b); }
; __device__ __forceinline__ void unpack8(const u32x4 w, float* f) { f[0] = bflo(w.x); f[1] = bfhi(w.x); f[2] = bflo(w.y); f[3] = bfhi(w.y); f[4] = bflo(w.z); f[5] = bfhi(w.z); f[6] = bflo(w.w); f[7] = bfhi(w.w); }
; __device__ __forceinline__ void hg_unit(const Ptrs& P, int l, int b, int hd, int ch, unsigned char* lds, int tid) {
;     ...
;         const int t = tid >> 2, sgm = tid & 3;
;         if (t < 16 * nsub) { const int j = t >> 4; bf16_t* qo = PJ + (row0 + t) * PW + C_HQ + hd * 128 + 32 * sgm;
; #pragma unroll
;             for (int c8 = 0; c8 < 4; ++c8) { const u32x4 qw = *(const u32x4*)(Qb + t * 136 + 32 * sgm + 8 * c8); float f[8]; unpack8(qw, f);
;                 const f32x4 d0 = *(const f32x4*)(DT + j * 128 + 32 * sgm + 8 * c8), d1 = *(const f32x4*)(DT + j * 128 + 32 * sgm + 8 * c8 + 4);
;                 u32x4 o; o.x = pk2(f[0] * d0[0], f[1] * d0[1]); o.y = pk2(f[2] * d0[2], f[3] * d0[3]); o.z = pk2(f[4] * d1[0], f[5] * d1[1]); o.w = pk2(f[6] * d1[2], f[7] * d1[3]);
;                 *(u32x4*)(qo + 8 * c8) = o; } }
.LBB0_601:
	s_or_b64 exec, exec, s[4:5]
	v_ashrrev_i32_e32 v10, 2, v98
	s_lshl_b32 s3, s6, 4
	v_cmp_gt_i32_e32 vcc, s3, v10
	s_waitcnt lgkmcnt(0)
	s_barrier
	s_and_saveexec_b64 s[4:5], vcc
	s_cbranch_execz .LBB0_603
	v_ashrrev_i32_e32 v11, 31, v10
	v_lshl_add_u64 v[18:19], s[44:45], 0, v[10:11]
	v_mad_u64_u32 v[20:21], s[6:7], v18, s34, v[86:87]
	v_lshlrev_b32_e32 v11, 3, v98
	v_mad_i32_i24 v21, v19, s34, v21
	v_and_b32_e32 v11, 0x18, v11
	v_lshl_add_u64 v[18:19], v[20:21], 0, s[96:97]
	v_lshlrev_b32_e32 v20, 1, v11
	v_mul_lo_u32 v10, v10, s26
	v_lshlrev_b32_e32 v17, 3, v98
	v_mov_b32_e32 v21, v16
	v_add3_u32 v10, 0, v10, v20
	v_and_b32_e32 v17, 0xfffffe00, v17
	v_lshlrev_b32_e32 v11, 2, v11
	v_readlane_b32 s3, v255, 28
	v_lshl_add_u64 v[30:31], v[18:19], 0, v[20:21]
	s_mov_b64 s[6:7], 0x2a00
	v_add3_u32 v17, s3, v17, v11
	ds_read_b128 v[18:21], v10
	ds_read_b128 v[22:25], v10 offset:64
	ds_read_b128 v[26:29], v10 offset:128
	ds_read_b128 v[34:37], v10 offset:192
	ds_read_b128 v[38:41], v17
	ds_read_b128 v[42:45], v17 offset:16
	ds_read_b128 v[52:55], v17 offset:128
	ds_read_b128 v[56:59], v17 offset:144
	s_waitcnt lgkmcnt(7)
	v_lshlrev_b32_e32 v10, 16, v18
	v_and_b32_e32 v11, 0xffff0000, v18
	s_waitcnt lgkmcnt(3)
	v_pk_mul_f32 v[10:11], v[38:39], v[10:11]
	s_movk_i32 s3, 0x2000
	v_cvt_pk_bf16_f32 v18, v10, v11
	v_lshlrev_b32_e32 v10, 16, v19
	v_and_b32_e32 v11, 0xffff0000, v19
	v_pk_mul_f32 v[10:11], v[40:41], v[10:11]
	v_lshl_add_u64 v[60:61], v[30:31], 0, s[6:7]
	v_cvt_pk_bf16_f32 v19, v10, v11
	v_lshlrev_b32_e32 v10, 16, v20
	v_and_b32_e32 v11, 0xffff0000, v20
	s_waitcnt lgkmcnt(2)
	v_pk_mul_f32 v[10:11], v[42:43], v[10:11]
	s_nop 0
	v_cvt_pk_bf16_f32 v20, v10, v11
	v_lshlrev_b32_e32 v10, 16, v21
	v_and_b32_e32 v11, 0xffff0000, v21
	v_pk_mul_f32 v[10:11], v[44:45], v[10:11]
	s_nop 0
	v_cvt_pk_bf16_f32 v21, v10, v11
	v_add_co_u32_e32 v10, vcc, s3, v30
	s_nop 1
	v_addc_co_u32_e32 v11, vcc, 0, v31, vcc
	global_store_dwordx4 v[10:11], v[18:21], off offset:2560
	v_lshlrev_b32_e32 v10, 16, v22
	v_and_b32_e32 v11, 0xffff0000, v22
	s_waitcnt lgkmcnt(1)
	v_pk_mul_f32 v[10:11], v[52:53], v[10:11]
	s_nop 0
	v_cvt_pk_bf16_f32 v18, v10, v11
	v_lshlrev_b32_e32 v10, 16, v23
	v_and_b32_e32 v11, 0xffff0000, v23
	v_pk_mul_f32 v[10:11], v[54:55], v[10:11]
	s_nop 0
	v_cvt_pk_bf16_f32 v19, v10, v11
	v_lshlrev_b32_e32 v10, 16, v24
	v_and_b32_e32 v11, 0xffff0000, v24
	s_waitcnt lgkmcnt(0)
	v_pk_mul_f32 v[10:11], v[56:57], v[10:11]
	s_nop 0
	v_cvt_pk_bf16_f32 v20, v10, v11
	v_lshlrev_b32_e32 v10, 16, v25
	v_and_b32_e32 v11, 0xffff0000, v25
	ds_read_b128 v[22:25], v17 offset:256
	v_pk_mul_f32 v[10:11], v[58:59], v[10:11]
	s_nop 0
	v_cvt_pk_bf16_f32 v21, v10, v11
	global_store_dwordx4 v[60:61], v[18:21], off offset:64
	ds_read_b128 v[18:21], v17 offset:272
	v_lshlrev_b32_e32 v10, 16, v26
	v_and_b32_e32 v11, 0xffff0000, v26
	s_waitcnt lgkmcnt(1)
	v_pk_mul_f32 v[10:11], v[22:23], v[10:11]
	s_nop 0
	v_cvt_pk_bf16_f32 v22, v10, v11
	v_lshlrev_b32_e32 v10, 16, v27
	v_and_b32_e32 v11, 0xffff0000, v27
	v_pk_mul_f32 v[10:11], v[24:25], v[10:11]
	s_nop 0
	v_cvt_pk_bf16_f32 v23, v10, v11
	v_lshlrev_b32_e32 v10, 16, v28
	v_and_b32_e32 v11, 0xffff0000, v28
	s_waitcnt lgkmcnt(0)
	v_pk_mul_f32 v[10:11], v[18:19], v[10:11]
	s_nop 0
	v_cvt_pk_bf16_f32 v24, v10, v11
	v_lshlrev_b32_e32 v10, 16, v29
	v_and_b32_e32 v11, 0xffff0000, v29
	v_pk_mul_f32 v[10:11], v[20:21], v[10:11]
	ds_read_b128 v[18:21], v17 offset:384
	v_cvt_pk_bf16_f32 v25, v10, v11
	global_store_dwordx4 v[60:61], v[22:25], off offset:128
	ds_read_b128 v[22:25], v17 offset:400
	v_lshlrev_b32_e32 v10, 16, v34
	v_and_b32_e32 v11, 0xffff0000, v34
	s_waitcnt lgkmcnt(1)
	v_pk_mul_f32 v[10:11], v[18:19], v[10:11]
	s_nop 0
	v_cvt_pk_bf16_f32 v18, v10, v11
	v_lshlrev_b32_e32 v10, 16, v35
	v_and_b32_e32 v11, 0xffff0000, v35
	v_pk_mul_f32 v[10:11], v[20:21], v[10:11]
	s_nop 0
	v_cvt_pk_bf16_f32 v19, v10, v11
	v_lshlrev_b32_e32 v10, 16, v36
	v_and_b32_e32 v11, 0xffff0000, v36
	s_waitcnt lgkmcnt(0)
	v_pk_mul_f32 v[10:11], v[22:23], v[10:11]
	s_nop 0
	v_cvt_pk_bf16_f32 v20, v10, v11
	v_lshlrev_b32_e32 v10, 16, v37
	v_and_b32_e32 v11, 0xffff0000, v37
	v_pk_mul_f32 v[10:11], v[24:25], v[10:11]
	s_nop 0
	v_cvt_pk_bf16_f32 v21, v10, v11
	global_store_dwordx4 v[60:61], v[18:21], off offset:192
